# GEMM K-loop: LDS-section address arithmetic hoisted into preceding MFMA blocks; first section's scalar pointer-select chain computed one iteration ahead inside the last MFMA block
# baseline (speedup 1.0000x reference)
; #define LDA(dst, b, h) for (int m = 0; m < 4; ++m) for (int k = 0; k < 2; ++k) \
;     dst[m][k] = *reinterpret_cast<const bf16x8*>(SA(b, h) + lds_byte(wr * 64 + m * 16 + fr, k * 32 + fq * 8))
; #define LDB(dst, b, h) for (int n = 0; n < 2; ++n) for (int k = 0; k < 2; ++k) \
;     dst[n][k] = *reinterpret_cast<const bf16x8*>(SB(b, h) + lds_byte(wc * 32 + n * 16 + fr, k * 32 + fq * 8))
; #define MMA(ai, bj, At_, Bt_) do { __builtin_amdgcn_s_setprio(1); \
;     for (int m = 0; m < 4; ++m) for (int n = 0; n < 2; ++n) for (int k = 0; k < 2; ++k) \
;       acc[ai][bj][m][n] = __builtin_amdgcn_mfma_f32_16x16x32_bf16(Bt_[n][k], At_[m][k], acc[ai][bj][m][n], 0, 0, 0); \
;     __builtin_amdgcn_s_setprio(0); } while (0)
; #define WAIT_V(n) asm volatile("s_waitcnt vmcnt(" #n ")" ::: "memory")
; #define WAIT_L(n) asm volatile("s_waitcnt lgkmcnt(" #n ")" ::: "memory")
; #define BAR __builtin_amdgcn_s_barrier()
; #define SCHED __builtin_amdgcn_sched_barrier(0)
; #define STG(P, PTR, LD, O0) do { const bf16_t* _g = (PTR); \
;     __builtin_amdgcn_global_load_lds((const unsigned*)(_g + O0), (lds_u32*)((P) + swave * 1024), 16, 0, 0); \
;     __builtin_amdgcn_global_load_lds((const unsigned*)(_g + (size_t)64 * (LD) + O0), (lds_u32*)((P) + swave * 1024 + 8192), 16, 0, 0); } while (0)
; __device__ __forceinline__ void gemm_stream(int swave, const GemmJob& J, char* shm, int vb, int G) {
;     ...
;     for (int t = 0; t < nt; t += 2) {
;       const bool last = (t == nt - 2);
;       const bf16_t* xA = last ? nA : cA; const bf16_t* xA1 = last ? nA1 : cA1; const int k2 = last ? 0 : t + 2;
;       const bf16_t* b2 = last ? nB : cB + (size_t)(t + 2) * 64; const bf16_t* b3 = b2 + 64;
;       LDB(B0, 0, 0); SCHED; LDA(At, 0, 0); STGA(SA(1, 1), cA, cA1, t + 1, 1);
;       WAIT_L(8); BAR; WAIT_L(0); MMA(0, 0, At, B0); BAR; SCHED;
;       LDB(B1, 0, 1); STG(SB(0, 0), b2, ldb, offB0);
;       BAR; WAIT_L(0); MMA(0, 1, At, B1); BAR;
;       LDA(At, 0, 1); STGA(SA(0, 0), xA, xA1, k2, 0);
;       BAR; WAIT_L(0); MMA(1, 0, At, B0); BAR; SCHED;
;       STG(SB(0, 1), b2 + hB, ldb, offB0);
;       WAIT_V(6); BAR; MMA(1, 1, At, B1); BAR;
;     ...
; #pragma unroll
;     for (int a_ = 0; a_ < 2; ++a_)
; #pragma unroll
;       for (int b_ = 0; b_ < 2; ++b_)
; #pragma unroll
;         for (int m = 0; m < 4; ++m)
; #pragma unroll
;           for (int n = 0; n < 2; ++n) acc[a_][b_][m][n] = (f32x4){0.f, 0.f, 0.f, 0.f};
.LBB0_728:
	s_add_u32 s20, s2, 0x100
	v_mov_b64_e32 v[4:5], 0
	v_mov_b64_e32 v[6:7], 0
	v_mov_b64_e32 v[8:9], 0
	v_mov_b64_e32 v[10:11], 0
	v_mov_b64_e32 v[12:13], 0
	v_mov_b64_e32 v[14:15], 0
	v_mov_b64_e32 v[16:17], 0
	v_mov_b64_e32 v[18:19], 0
	v_mov_b64_e32 v[20:21], 0
	v_mov_b64_e32 v[22:23], 0
	v_mov_b64_e32 v[24:25], 0
	v_mov_b64_e32 v[26:27], 0
	v_mov_b64_e32 v[28:29], 0
	v_mov_b64_e32 v[30:31], 0
	v_mov_b64_e32 v[32:33], 0
	v_mov_b64_e32 v[34:35], 0
	v_mov_b64_e32 v[36:37], 0
	v_mov_b64_e32 v[38:39], 0
	v_mov_b64_e32 v[40:41], 0
	v_mov_b64_e32 v[42:43], 0
	v_mov_b64_e32 v[44:45], 0
	v_mov_b64_e32 v[46:47], 0
	v_mov_b64_e32 v[48:49], 0
	v_mov_b64_e32 v[50:51], 0
	v_mov_b64_e32 v[52:53], 0
	v_mov_b64_e32 v[54:55], 0
	v_mov_b64_e32 v[56:57], 0
	v_mov_b64_e32 v[58:59], 0
	v_mov_b64_e32 v[60:61], 0
	v_mov_b64_e32 v[62:63], 0
	v_mov_b64_e32 v[64:65], 0
	v_mov_b64_e32 v[66:67], 0
	v_mov_b64_e32 v[68:69], 0
	v_mov_b64_e32 v[70:71], 0
	v_mov_b64_e32 v[72:73], 0
	v_mov_b64_e32 v[74:75], 0
	v_mov_b64_e32 v[76:77], 0
	v_mov_b64_e32 v[78:79], 0
	v_mov_b64_e32 v[80:81], 0
	v_mov_b64_e32 v[82:83], 0
	v_mov_b64_e32 v[84:85], 0
	v_mov_b64_e32 v[86:87], 0
	v_mov_b64_e32 v[88:89], 0
	v_mov_b64_e32 v[90:91], 0
	v_mov_b64_e32 v[92:93], 0
	v_mov_b64_e32 v[94:95], 0
	v_mov_b64_e32 v[96:97], 0
	v_mov_b64_e32 v[98:99], 0
	v_mov_b64_e32 v[100:101], 0
	v_mov_b64_e32 v[102:103], 0
	v_mov_b64_e32 v[104:105], 0
	v_mov_b64_e32 v[106:107], 0
	v_mov_b64_e32 v[108:109], 0
	v_mov_b64_e32 v[110:111], 0
	v_mov_b64_e32 v[112:113], 0
	v_mov_b64_e32 v[114:115], 0
	v_mov_b64_e32 v[116:117], 0
	v_mov_b64_e32 v[118:119], 0
	v_mov_b64_e32 v[120:121], 0
	v_mov_b64_e32 v[122:123], 0
	v_mov_b64_e32 v[124:125], 0
	v_mov_b64_e32 v[126:127], 0
	v_mov_b64_e32 v[128:129], 0
	v_mov_b64_e32 v[130:131], 0
	s_addc_u32 s21, s3, 0
	s_mov_b32 s2, 0
	s_mov_b32 s29, 2
	s_cmp_eq_u32 s49, s29
	s_cselect_b64 s[68:69], -1, 0
	s_and_b64 s[64:65], s[68:69], exec
	s_cselect_b32 s52, s10, s8
	s_cselect_b32 s64, s11, s9
	s_add_i32 s33, s2, 2
	s_and_b64 s[68:69], s[68:69], exec
	s_cselect_b32 s71, s15, s21
	s_cselect_b32 s70, s14, s20
	s_cselect_b32 s68, 0, s33
	s_cselect_b32 s65, s12, s16
	s_cselect_b32 s66, s13, s17
	s_or_b32 s2, s2, 1
	s_cmp_lt_u32 s2, s36
	s_cselect_b64 vcc, -1, 0
	s_and_b64 s[2:3], vcc, exec
	s_cselect_b32 s3, 0, s36
	s_cselect_b32 s2, s38, s37
	s_not_b32 s3, s3
	s_add_i32 s94, s3, s29
	s_and_b64 s[72:73], vcc, exec
	s_cselect_b32 s3, s9, s17
	s_cselect_b32 s69, s8, s16
	s_lshl_b64 s[72:73], s[94:95], 7
	s_add_u32 s69, s69, s72
	s_addc_u32 s74, s3, s73
	s_mov_b32 s3, s95
	s_lshl_b64 s[72:73], s[2:3], 8
	s_add_u32 s72, s69, s72
	s_addc_u32 s73, s74, s73
	s_add_i32 m0, s42, 0xc000
	s_lshl_b64 s[2:3], s[2:3], 7
	s_add_u32 s2, s72, s2
	s_addc_u32 s3, s73, s3
.LBB0_729:
	ds_read_b128 v[164:167], v139
	ds_read_b128 v[168:171], v139 offset:1024
	ds_read_b128 v[172:175], v139 offset:2048
	ds_read_b128 v[176:179], v139 offset:3072
	v_cndmask_b32_e32 v2, v138, v0, vcc
	v_lshlrev_b64 v[212:213], 1, v[2:3]
	v_lshl_add_u64 v[214:215], s[72:73], 0, v[212:213]
	ds_read_b128 v[180:183], v144
	ds_read_b128 v[184:187], v144 offset:1024
	ds_read_b128 v[188:191], v145
	ds_read_b128 v[192:195], v145 offset:1024
	ds_read_b128 v[196:199], v159
	ds_read_b128 v[200:203], v159 offset:1024
	ds_read_b128 v[204:207], v160
	ds_read_b128 v[208:211], v160 offset:1024
	global_load_lds_dwordx4 v[214:215], off
	v_lshl_add_u64 v[212:213], s[2:3], 0, v[212:213]
	s_add_i32 m0, s42, 0xe000
	s_nop 0
	global_load_lds_dwordx4 v[212:213], off
	s_waitcnt lgkmcnt(8)
	s_barrier
	s_waitcnt lgkmcnt(0)
	s_waitcnt lgkmcnt(0)
	v_mfma_f32_16x16x32_bf16 v[128:131], v[164:167], v[180:183], v[128:131]
	v_mfma_f32_16x16x32_bf16 v[124:127], v[172:175], v[180:183], v[124:127]
	s_add_u32 s2, s70, s0
	v_mfma_f32_16x16x32_bf16 v[120:123], v[164:167], v[188:191], v[120:123]
	s_mov_b32 m0, s43
	v_mfma_f32_16x16x32_bf16 v[116:119], v[172:175], v[188:191], v[116:119]
	v_lshl_add_u64 v[228:229], s[70:71], 0, v[136:137]
	v_mfma_f32_16x16x32_bf16 v[104:107], v[164:167], v[196:199], v[104:107]
	s_addc_u32 s3, s71, s1
	v_mfma_f32_16x16x32_bf16 v[100:103], v[172:175], v[196:199], v[100:103]
	v_mfma_f32_16x16x32_bf16 v[88:91], v[164:167], v[204:207], v[88:91]
	v_mfma_f32_16x16x32_bf16 v[84:87], v[172:175], v[204:207], v[84:87]
	v_mfma_f32_16x16x32_bf16 v[128:131], v[168:171], v[184:187], v[128:131]
	v_mfma_f32_16x16x32_bf16 v[124:127], v[176:179], v[184:187], v[124:127]
	v_mfma_f32_16x16x32_bf16 v[120:123], v[168:171], v[192:195], v[120:123]
	v_mfma_f32_16x16x32_bf16 v[116:119], v[176:179], v[192:195], v[116:119]
	v_mfma_f32_16x16x32_bf16 v[104:107], v[168:171], v[200:203], v[104:107]
	v_mfma_f32_16x16x32_bf16 v[100:103], v[176:179], v[200:203], v[100:103]
	v_mfma_f32_16x16x32_bf16 v[88:91], v[168:171], v[208:211], v[88:91]
	v_mfma_f32_16x16x32_bf16 v[84:87], v[176:179], v[208:211], v[84:87]
	s_barrier
	ds_read_b128 v[212:215], v161
	ds_read_b128 v[216:219], v161 offset:1024
	ds_read_b128 v[220:223], v161 offset:2048
	ds_read_b128 v[224:227], v161 offset:3072
	global_load_lds_dwordx4 v[228:229], off
	v_lshl_add_u64 v[230:231], s[2:3], 0, v[136:137]
	s_mov_b32 m0, s44
	s_nop 0
	global_load_lds_dwordx4 v[230:231], off
	s_barrier
; #define LDA(dst, b, h) for (int m = 0; m < 4; ++m) for (int k = 0; k < 2; ++k) \
;     dst[m][k] = *reinterpret_cast<const bf16x8*>(SA(b, h) + lds_byte(wr * 64 + m * 16 + fr, k * 32 + fq * 8))
; #define LDB(dst, b, h) for (int n = 0; n < 2; ++n) for (int k = 0; k < 2; ++k) \
;     dst[n][k] = *reinterpret_cast<const bf16x8*>(SB(b, h) + lds_byte(wc * 32 + n * 16 + fr, k * 32 + fq * 8))
; #define MMA(ai, bj, At_, Bt_) do { __builtin_amdgcn_s_setprio(1); \
;     for (int m = 0; m < 4; ++m) for (int n = 0; n < 2; ++n) for (int k = 0; k < 2; ++k) \
;       acc[ai][bj][m][n] = __builtin_amdgcn_mfma_f32_16x16x32_bf16(Bt_[n][k], At_[m][k], acc[ai][bj][m][n], 0, 0, 0); \
;     __builtin_amdgcn_s_setprio(0); } while (0)
; #define WAIT_V(n) asm volatile("s_waitcnt vmcnt(" #n ")" ::: "memory")
; #define WAIT_L(n) asm volatile("s_waitcnt lgkmcnt(" #n ")" ::: "memory")
; #define BAR __builtin_amdgcn_s_barrier()
; #define SCHED __builtin_amdgcn_sched_barrier(0)
; #define STG(P, PTR, LD, O0) do { const bf16_t* _g = (PTR); \
;     __builtin_amdgcn_global_load_lds((const unsigned*)(_g + O0), (lds_u32*)((P) + swave * 1024), 16, 0, 0); \
;     __builtin_amdgcn_global_load_lds((const unsigned*)(_g + (size_t)64 * (LD) + O0), (lds_u32*)((P) + swave * 1024 + 8192), 16, 0, 0); } while (0)
; #define LDA(dst, b, h) for (int m = 0; m < 4; ++m) for (int k = 0; k < 2; ++k) \
;     dst[m][k] = *reinterpret_cast<const bf16x8*>(SA(b, h) + lds_byte(wr * 64 + m * 16 + fr, k * 32 + fq * 8))
; #define LDB(dst, b, h) for (int n = 0; n < 2; ++n) for (int k = 0; k < 2; ++k) \
;     dst[n][k] = *reinterpret_cast<const bf16x8*>(SB(b, h) + lds_byte(wc * 32 + n * 16 + fr, k * 32 + fq * 8))
; #define WAIT_V(n) asm volatile("s_waitcnt vmcnt(" #n ")" ::: "memory")
; __device__ __forceinline__ void gemm_stream(int swave, const GemmJob& J, char* shm, int vb, int G) {
;     ...
;       WAIT_L(8); BAR; WAIT_L(0); MMA(0, 0, At, B0); BAR; SCHED;
;       LDB(B1, 0, 1); STG(SB(0, 0), b2, ldb, offB0);
;       BAR; WAIT_L(0); MMA(0, 1, At, B1); BAR;
;       LDA(At, 0, 1); STGA(SA(0, 0), xA, xA1, k2, 0);
;       BAR; WAIT_L(0); MMA(1, 0, At, B0); BAR; SCHED;
;       STG(SB(0, 1), b2 + hB, ldb, offB0);
;       WAIT_V(6); BAR; MMA(1, 1, At, B1); BAR;
;       LDB(B0, 1, 0); SCHED; LDA(At, 1, 0); STGA(SA(0, 1), xA, xA1, k2, 1);
;       WAIT_L(8); BAR; WAIT_L(0); MMA(0, 0, At, B0); BAR; SCHED;
	s_waitcnt lgkmcnt(0)
	s_waitcnt lgkmcnt(0)
	v_mfma_f32_16x16x32_bf16 v[112:115], v[212:215], v[180:183], v[112:115]
	v_mfma_f32_16x16x32_bf16 v[108:111], v[220:223], v[180:183], v[108:111]
	s_cmp_lt_u32 s68, s36
	s_cselect_b64 vcc, -1, 0
	v_mfma_f32_16x16x32_bf16 v[96:99], v[212:215], v[188:191], v[96:99]
	s_and_b64 s[70:71], vcc, exec
	s_cselect_b32 s70, s38, s37
	v_mfma_f32_16x16x32_bf16 v[92:95], v[220:223], v[188:191], v[92:95]
	s_sub_i32 s69, s68, s36
	s_min_u32 s94, s68, s69
	v_mfma_f32_16x16x32_bf16 v[80:83], v[212:215], v[196:199], v[80:83]
	s_and_b64 s[72:73], vcc, exec
	s_cselect_b32 s69, s64, s66
	v_mfma_f32_16x16x32_bf16 v[76:79], v[220:223], v[196:199], v[76:79]
	s_cselect_b32 s71, s52, s65
	s_lshl_b64 s[72:73], s[94:95], 7
	v_mfma_f32_16x16x32_bf16 v[72:75], v[212:215], v[204:207], v[72:75]
	v_cndmask_b32_e32 v2, v138, v0, vcc
	s_add_u32 s72, s71, s72
	v_mfma_f32_16x16x32_bf16 v[68:71], v[220:223], v[204:207], v[68:71]
	s_mov_b32 s71, s95
	v_mfma_f32_16x16x32_bf16 v[112:115], v[216:219], v[184:187], v[112:115]
	s_addc_u32 s73, s69, s73
	v_mfma_f32_16x16x32_bf16 v[108:111], v[224:227], v[184:187], v[108:111]
	v_lshlrev_b64 v[232:233], 1, v[2:3]
	v_mfma_f32_16x16x32_bf16 v[96:99], v[216:219], v[192:195], v[96:99]
	s_lshl_b64 s[70:71], s[70:71], 7
	v_mfma_f32_16x16x32_bf16 v[92:95], v[224:227], v[192:195], v[92:95]
	v_lshl_add_u64 v[234:235], s[72:73], 0, v[232:233]
	v_mfma_f32_16x16x32_bf16 v[80:83], v[216:219], v[200:203], v[80:83]
	s_add_u32 s72, s72, s70
	v_mfma_f32_16x16x32_bf16 v[76:79], v[224:227], v[200:203], v[76:79]
	s_mov_b32 m0, s42
	v_mfma_f32_16x16x32_bf16 v[72:75], v[216:219], v[208:211], v[72:75]
	s_addc_u32 s73, s73, s71
	v_mfma_f32_16x16x32_bf16 v[68:71], v[224:227], v[208:211], v[68:71]
	s_barrier
	ds_read_b128 v[180:183], v144 offset:16384
	ds_read_b128 v[184:187], v144 offset:17408
	ds_read_b128 v[188:191], v145 offset:16384
	ds_read_b128 v[192:195], v145 offset:17408
	ds_read_b128 v[196:199], v159 offset:16384
	ds_read_b128 v[200:203], v159 offset:17408
	ds_read_b128 v[204:207], v160 offset:16384
	ds_read_b128 v[208:211], v160 offset:17408
	global_load_lds_dwordx4 v[234:235], off
	v_lshl_add_u64 v[234:235], s[72:73], 0, v[232:233]
	s_mov_b32 m0, s39
	s_nop 0
	global_load_lds_dwordx4 v[234:235], off
	s_barrier
	s_waitcnt lgkmcnt(0)
	s_waitcnt lgkmcnt(0)
	v_mfma_f32_16x16x32_bf16 v[64:67], v[164:167], v[180:183], v[64:67]
	v_mfma_f32_16x16x32_bf16 v[60:63], v[172:175], v[180:183], v[60:63]
	s_add_u32 s2, s2, s0
	v_mfma_f32_16x16x32_bf16 v[56:59], v[164:167], v[188:191], v[56:59]
	s_addc_u32 s3, s3, s1
	v_mfma_f32_16x16x32_bf16 v[52:55], v[172:175], v[188:191], v[52:55]
	v_lshl_add_u64 v[234:235], s[2:3], 0, v[136:137]
	v_mfma_f32_16x16x32_bf16 v[40:43], v[164:167], v[196:199], v[40:43]
	s_add_u32 s2, s2, s0
	v_mfma_f32_16x16x32_bf16 v[36:39], v[172:175], v[196:199], v[36:39]
	s_mov_b32 m0, s45
	v_mfma_f32_16x16x32_bf16 v[24:27], v[164:167], v[204:207], v[24:27]
	s_addc_u32 s3, s3, s1
	v_mfma_f32_16x16x32_bf16 v[20:23], v[172:175], v[204:207], v[20:23]
	v_mfma_f32_16x16x32_bf16 v[64:67], v[168:171], v[184:187], v[64:67]
	v_mfma_f32_16x16x32_bf16 v[60:63], v[176:179], v[184:187], v[60:63]
	v_mfma_f32_16x16x32_bf16 v[56:59], v[168:171], v[192:195], v[56:59]
	v_mfma_f32_16x16x32_bf16 v[52:55], v[176:179], v[192:195], v[52:55]
	v_mfma_f32_16x16x32_bf16 v[40:43], v[168:171], v[200:203], v[40:43]
	v_mfma_f32_16x16x32_bf16 v[36:39], v[176:179], v[200:203], v[36:39]
	v_mfma_f32_16x16x32_bf16 v[24:27], v[168:171], v[208:211], v[24:27]
	v_mfma_f32_16x16x32_bf16 v[20:23], v[176:179], v[208:211], v[20:23]
	s_barrier
	global_load_lds_dwordx4 v[234:235], off
	v_lshl_add_u64 v[236:237], s[2:3], 0, v[136:137]
	s_mov_b32 m0, s46
	s_nop 0
	global_load_lds_dwordx4 v[236:237], off
	s_waitcnt vmcnt(6)
	s_barrier
	v_mfma_f32_16x16x32_bf16 v[48:51], v[212:215], v[180:183], v[48:51]
	v_mfma_f32_16x16x32_bf16 v[44:47], v[220:223], v[180:183], v[44:47]
	s_add_u32 s2, s72, s70
	v_mfma_f32_16x16x32_bf16 v[32:35], v[212:215], v[188:191], v[32:35]
	s_addc_u32 s3, s73, s71
	v_mfma_f32_16x16x32_bf16 v[28:31], v[220:223], v[188:191], v[28:31]
	v_mfma_f32_16x16x32_bf16 v[16:19], v[212:215], v[196:199], v[16:19]
	v_mfma_f32_16x16x32_bf16 v[12:15], v[220:223], v[196:199], v[12:15]
	v_mfma_f32_16x16x32_bf16 v[8:11], v[212:215], v[204:207], v[8:11]
	v_mfma_f32_16x16x32_bf16 v[4:7], v[220:223], v[204:207], v[4:7]
	v_mfma_f32_16x16x32_bf16 v[48:51], v[216:219], v[184:187], v[48:51]
	v_mfma_f32_16x16x32_bf16 v[44:47], v[224:227], v[184:187], v[44:47]
	v_mfma_f32_16x16x32_bf16 v[32:35], v[216:219], v[192:195], v[32:35]
	v_mfma_f32_16x16x32_bf16 v[28:31], v[224:227], v[192:195], v[28:31]
	v_mfma_f32_16x16x32_bf16 v[16:19], v[216:219], v[200:203], v[16:19]
	v_mfma_f32_16x16x32_bf16 v[12:15], v[224:227], v[200:203], v[12:15]
	v_mfma_f32_16x16x32_bf16 v[8:11], v[216:219], v[208:211], v[8:11]
	v_mfma_f32_16x16x32_bf16 v[4:7], v[224:227], v[208:211], v[4:7]
	s_barrier
	ds_read_b128 v[164:167], v162
	ds_read_b128 v[168:171], v162 offset:1024
	ds_read_b128 v[172:175], v162 offset:2048
	ds_read_b128 v[176:179], v162 offset:3072
	v_lshl_add_u64 v[212:213], s[2:3], 0, v[232:233]
	s_add_u32 s2, s2, s70
	s_mov_b32 m0, s47
	s_addc_u32 s3, s3, s71
	ds_read_b128 v[180:183], v144 offset:32768
	ds_read_b128 v[184:187], v144 offset:33792
	ds_read_b128 v[188:191], v145 offset:32768
	ds_read_b128 v[192:195], v145 offset:33792
	ds_read_b128 v[196:199], v159 offset:32768
	ds_read_b128 v[200:203], v159 offset:33792
	ds_read_b128 v[204:207], v160 offset:32768
	ds_read_b128 v[208:211], v160 offset:33792
	global_load_lds_dwordx4 v[212:213], off
	v_lshl_add_u64 v[212:213], s[2:3], 0, v[232:233]
	s_mov_b32 m0, s48
	s_nop 0
	global_load_lds_dwordx4 v[212:213], off
	s_waitcnt lgkmcnt(8)
	s_barrier
; #define LDA(dst, b, h) for (int m = 0; m < 4; ++m) for (int k = 0; k < 2; ++k) \
;     dst[m][k] = *reinterpret_cast<const bf16x8*>(SA(b, h) + lds_byte(wr * 64 + m * 16 + fr, k * 32 + fq * 8))
; #define LDB(dst, b, h) for (int n = 0; n < 2; ++n) for (int k = 0; k < 2; ++k) \
;     dst[n][k] = *reinterpret_cast<const bf16x8*>(SB(b, h) + lds_byte(wc * 32 + n * 16 + fr, k * 32 + fq * 8))
; #define MMA(ai, bj, At_, Bt_) do { __builtin_amdgcn_s_setprio(1); \
;     for (int m = 0; m < 4; ++m) for (int n = 0; n < 2; ++n) for (int k = 0; k < 2; ++k) \
;       acc[ai][bj][m][n] = __builtin_amdgcn_mfma_f32_16x16x32_bf16(Bt_[n][k], At_[m][k], acc[ai][bj][m][n], 0, 0, 0); \
;     __builtin_amdgcn_s_setprio(0); } while (0)
; #define WAIT_V(n) asm volatile("s_waitcnt vmcnt(" #n ")" ::: "memory")
; #define WAIT_L(n) asm volatile("s_waitcnt lgkmcnt(" #n ")" ::: "memory")
; #define BAR __builtin_amdgcn_s_barrier()
; #define SCHED __builtin_amdgcn_sched_barrier(0)
; #define STG(P, PTR, LD, O0) do { const bf16_t* _g = (PTR); \
;     __builtin_amdgcn_global_load_lds((const unsigned*)(_g + O0), (lds_u32*)((P) + swave * 1024), 16, 0, 0); \
;     __builtin_amdgcn_global_load_lds((const unsigned*)(_g + (size_t)64 * (LD) + O0), (lds_u32*)((P) + swave * 1024 + 8192), 16, 0, 0); } while (0)
; #define LDA(dst, b, h) for (int m = 0; m < 4; ++m) for (int k = 0; k < 2; ++k) \
;     dst[m][k] = *reinterpret_cast<const bf16x8*>(SA(b, h) + lds_byte(wr * 64 + m * 16 + fr, k * 32 + fq * 8))
; #define LDB(dst, b, h) for (int n = 0; n < 2; ++n) for (int k = 0; k < 2; ++k) \
;     dst[n][k] = *reinterpret_cast<const bf16x8*>(SB(b, h) + lds_byte(wc * 32 + n * 16 + fr, k * 32 + fq * 8))
; #define WAIT_V(n) asm volatile("s_waitcnt vmcnt(" #n ")" ::: "memory")
; #define WAIT_L(n) asm volatile("s_waitcnt lgkmcnt(" #n ")" ::: "memory")
; #define BAR __builtin_amdgcn_s_barrier()
; #define SCHED __builtin_amdgcn_sched_barrier(0)
; __device__ __forceinline__ void gemm_stream(int swave, const GemmJob& J, char* shm, int vb, int G) {
;     ...
;       WAIT_L(8); BAR; WAIT_L(0); MMA(0, 0, At, B0); BAR; SCHED;
;       LDB(B1, 1, 1); STG(SB(1, 0), b3, ldb, offB0);
;       BAR; WAIT_L(0); MMA(0, 1, At, B1); BAR;
;       LDA(At, 1, 1); STGA(SA(1, 0), xA, xA1, k2 + 1, 0);
;       BAR; WAIT_L(0); MMA(1, 0, At, B0); BAR; SCHED;
;       STG(SB(1, 1), b3 + hB, ldb, offB0);
;       WAIT_V(6); BAR; MMA(1, 1, At, B1); BAR;
	s_waitcnt lgkmcnt(0)
	s_waitcnt lgkmcnt(0)
	v_mfma_f32_16x16x32_bf16 v[128:131], v[164:167], v[180:183], v[128:131]
	v_mfma_f32_16x16x32_bf16 v[124:127], v[172:175], v[180:183], v[124:127]
	v_lshl_add_u64 v[228:229], v[228:229], 0, s[22:23]
	v_mfma_f32_16x16x32_bf16 v[120:123], v[164:167], v[188:191], v[120:123]
	s_add_i32 m0, s42, 0x18000
	v_mfma_f32_16x16x32_bf16 v[116:119], v[172:175], v[188:191], v[116:119]
	v_mfma_f32_16x16x32_bf16 v[104:107], v[164:167], v[196:199], v[104:107]
	v_mfma_f32_16x16x32_bf16 v[100:103], v[172:175], v[196:199], v[100:103]
	v_mfma_f32_16x16x32_bf16 v[88:91], v[164:167], v[204:207], v[88:91]
	v_mfma_f32_16x16x32_bf16 v[84:87], v[172:175], v[204:207], v[84:87]
	v_mfma_f32_16x16x32_bf16 v[128:131], v[168:171], v[184:187], v[128:131]
	v_mfma_f32_16x16x32_bf16 v[124:127], v[176:179], v[184:187], v[124:127]
	v_mfma_f32_16x16x32_bf16 v[120:123], v[168:171], v[192:195], v[120:123]
	v_mfma_f32_16x16x32_bf16 v[116:119], v[176:179], v[192:195], v[116:119]
	v_mfma_f32_16x16x32_bf16 v[104:107], v[168:171], v[200:203], v[104:107]
	v_mfma_f32_16x16x32_bf16 v[100:103], v[176:179], v[200:203], v[100:103]
	v_mfma_f32_16x16x32_bf16 v[88:91], v[168:171], v[208:211], v[88:91]
	v_mfma_f32_16x16x32_bf16 v[84:87], v[176:179], v[208:211], v[84:87]
	s_barrier
	ds_read_b128 v[212:215], v163
	ds_read_b128 v[216:219], v163 offset:1024
	ds_read_b128 v[220:223], v163 offset:2048
	ds_read_b128 v[224:227], v163 offset:3072
	global_load_lds_dwordx4 v[228:229], off
	v_lshl_add_u64 v[228:229], v[230:231], 0, s[22:23]
	s_add_i32 m0, s42, 0x1a000
	s_nop 0
	global_load_lds_dwordx4 v[228:229], off
	s_barrier
	s_waitcnt lgkmcnt(0)
	s_waitcnt lgkmcnt(0)
	v_mfma_f32_16x16x32_bf16 v[112:115], v[212:215], v[180:183], v[112:115]
	v_mfma_f32_16x16x32_bf16 v[108:111], v[220:223], v[180:183], v[108:111]
	s_or_b32 s68, s68, 1
	s_cmp_lt_u32 s68, s36
	v_mfma_f32_16x16x32_bf16 v[96:99], v[212:215], v[188:191], v[96:99]
	s_cselect_b64 vcc, -1, 0
	s_and_b64 s[2:3], vcc, exec
	v_mfma_f32_16x16x32_bf16 v[92:95], v[220:223], v[188:191], v[92:95]
	s_cselect_b32 s69, s38, s37
	s_sub_i32 s2, s68, s36
	v_mfma_f32_16x16x32_bf16 v[80:83], v[212:215], v[196:199], v[80:83]
	s_min_u32 s94, s68, s2
	s_and_b64 s[2:3], vcc, exec
	v_mfma_f32_16x16x32_bf16 v[76:79], v[220:223], v[196:199], v[76:79]
	s_cselect_b32 s64, s64, s66
	s_cselect_b32 s52, s52, s65
	v_mfma_f32_16x16x32_bf16 v[72:75], v[212:215], v[204:207], v[72:75]
	s_lshl_b64 s[2:3], s[94:95], 7
	v_cndmask_b32_e32 v2, v138, v0, vcc
	v_mfma_f32_16x16x32_bf16 v[68:71], v[220:223], v[204:207], v[68:71]
	s_add_u32 s2, s52, s2
	v_mfma_f32_16x16x32_bf16 v[112:115], v[216:219], v[184:187], v[112:115]
	s_addc_u32 s3, s64, s3
	v_mfma_f32_16x16x32_bf16 v[108:111], v[224:227], v[184:187], v[108:111]
	v_lshlrev_b64 v[228:229], 1, v[2:3]
	v_mfma_f32_16x16x32_bf16 v[96:99], v[216:219], v[192:195], v[96:99]
	s_lshl_b32 s52, s69, 7
	v_mfma_f32_16x16x32_bf16 v[92:95], v[224:227], v[192:195], v[92:95]
	v_lshl_add_u64 v[230:231], s[2:3], 0, v[228:229]
	v_mfma_f32_16x16x32_bf16 v[80:83], v[216:219], v[200:203], v[80:83]
	s_add_u32 s2, s2, s52
	v_mfma_f32_16x16x32_bf16 v[76:79], v[224:227], v[200:203], v[76:79]
	s_mov_b32 m0, s54
	v_mfma_f32_16x16x32_bf16 v[72:75], v[216:219], v[208:211], v[72:75]
	s_addc_u32 s3, s3, 0
	v_mfma_f32_16x16x32_bf16 v[68:71], v[224:227], v[208:211], v[68:71]
	s_barrier
	ds_read_b128 v[180:183], v144 offset:49152
	ds_read_b128 v[184:187], v144 offset:50176
	ds_read_b128 v[188:191], v145 offset:49152
	ds_read_b128 v[192:195], v145 offset:50176
	ds_read_b128 v[196:199], v159 offset:49152
	ds_read_b128 v[200:203], v159 offset:50176
	ds_read_b128 v[204:207], v160 offset:49152
	ds_read_b128 v[208:211], v160 offset:50176
	global_load_lds_dwordx4 v[230:231], off
	v_lshl_add_u64 v[228:229], s[2:3], 0, v[228:229]
	s_mov_b32 m0, s55
	s_nop 0
	global_load_lds_dwordx4 v[228:229], off
	s_barrier
	s_waitcnt lgkmcnt(0)
	s_waitcnt lgkmcnt(0)
	v_mfma_f32_16x16x32_bf16 v[64:67], v[164:167], v[180:183], v[64:67]
	v_mfma_f32_16x16x32_bf16 v[60:63], v[172:175], v[180:183], v[60:63]
	v_mfma_f32_16x16x32_bf16 v[56:59], v[164:167], v[188:191], v[56:59]
	v_mfma_f32_16x16x32_bf16 v[52:55], v[172:175], v[188:191], v[52:55]
	v_mfma_f32_16x16x32_bf16 v[40:43], v[164:167], v[196:199], v[40:43]
	v_mfma_f32_16x16x32_bf16 v[36:39], v[172:175], v[196:199], v[36:39]
	v_mfma_f32_16x16x32_bf16 v[24:27], v[164:167], v[204:207], v[24:27]
	v_mfma_f32_16x16x32_bf16 v[20:23], v[172:175], v[204:207], v[20:23]
	v_mfma_f32_16x16x32_bf16 v[64:67], v[168:171], v[184:187], v[64:67]
	v_mfma_f32_16x16x32_bf16 v[60:63], v[176:179], v[184:187], v[60:63]
	v_mfma_f32_16x16x32_bf16 v[56:59], v[168:171], v[192:195], v[56:59]
	v_mfma_f32_16x16x32_bf16 v[52:55], v[176:179], v[192:195], v[52:55]
	v_mfma_f32_16x16x32_bf16 v[40:43], v[168:171], v[200:203], v[40:43]
	v_mfma_f32_16x16x32_bf16 v[36:39], v[176:179], v[200:203], v[36:39]
	v_mfma_f32_16x16x32_bf16 v[24:27], v[168:171], v[208:211], v[24:27]
	v_mfma_f32_16x16x32_bf16 v[20:23], v[176:179], v[208:211], v[20:23]
	s_barrier
	v_lshl_add_u64 v[164:165], v[234:235], 0, s[22:23]
	s_add_i32 m0, s42, 0x1c000
	s_nop 0
	global_load_lds_dwordx4 v[164:165], off
	v_lshl_add_u64 v[164:165], v[236:237], 0, s[22:23]
	s_add_i32 m0, s42, 0x1e000
	s_nop 0
	global_load_lds_dwordx4 v[164:165], off
	s_waitcnt vmcnt(6)
	s_barrier
; __device__ __forceinline__ unsigned pk2(float lo, float hi) { f32x2_t v = {lo, hi}; bf16x2_t b = __builtin_convertvector(v, bf16x2_t); return __builtin_bit_cast(unsigned, b); }
; #define LDA(dst, b, h) for (int m = 0; m < 4; ++m) for (int k = 0; k < 2; ++k) \
;     dst[m][k] = *reinterpret_cast<const bf16x8*>(SA(b, h) + lds_byte(wr * 64 + m * 16 + fr, k * 32 + fq * 8))
; #define LDB(dst, b, h) for (int n = 0; n < 2; ++n) for (int k = 0; k < 2; ++k) \
;     dst[n][k] = *reinterpret_cast<const bf16x8*>(SB(b, h) + lds_byte(wc * 32 + n * 16 + fr, k * 32 + fq * 8))
; #define MMA(ai, bj, At_, Bt_) do { __builtin_amdgcn_s_setprio(1); \
;     for (int m = 0; m < 4; ++m) for (int n = 0; n < 2; ++n) for (int k = 0; k < 2; ++k) \
;       acc[ai][bj][m][n] = __builtin_amdgcn_mfma_f32_16x16x32_bf16(Bt_[n][k], At_[m][k], acc[ai][bj][m][n], 0, 0, 0); \
;     __builtin_amdgcn_s_setprio(0); } while (0)
; #define WAIT_V(n) asm volatile("s_waitcnt vmcnt(" #n ")" ::: "memory")
; #define BAR __builtin_amdgcn_s_barrier()
; #define SCHED __builtin_amdgcn_sched_barrier(0)
; #define LDA(dst, b, h) for (int m = 0; m < 4; ++m) for (int k = 0; k < 2; ++k) \
;     dst[m][k] = *reinterpret_cast<const bf16x8*>(SA(b, h) + lds_byte(wr * 64 + m * 16 + fr, k * 32 + fq * 8))
; #define BAR __builtin_amdgcn_s_barrier()
; __device__ __forceinline__ void gemm_stream(int swave, const GemmJob& J, char* shm, int vb, int G) {
;     ...
;       const bool last = (t == nt - 2);
;       const bf16_t* xA = last ? nA : cA; const bf16_t* xA1 = last ? nA1 : cA1; const int k2 = last ? 0 : t + 2;
;       const bf16_t* b2 = last ? nB : cB + (size_t)(t + 2) * 64; const bf16_t* b3 = b2 + 64;
;       LDB(B0, 0, 0); SCHED; LDA(At, 0, 0); STGA(SA(1, 1), cA, cA1, t + 1, 1);
;     ...
;       WAIT_V(6); BAR; MMA(1, 1, At, B1); BAR;
;     }
;     {
;       bf16_t* C = (bf16_t*)((char*)J.c0 + (size_t)cg * J.strideC);
; #pragma unroll
;       for (int ai = 0; ai < 2; ++ai)
; #pragma unroll
;         for (int m = 0; m < 4; ++m)
; #pragma unroll
;           for (int bj = 0; bj < 2; ++bj) {
;             const f32x4 v0 = acc[ai][bj][m][0], v1 = acc[ai][bj][m][1];
;             uint4 o; o.x = pk2(v0[0], v0[1]); o.y = pk2(v0[2], v0[3]); o.z = pk2(v1[0], v1[1]); o.w = pk2(v1[2], v1[3]);
;             *(uint4*)(C + (size_t)(cbrow + ai * 128 + wr * 64 + m * 16 + fr) * J.ldc + cbcol + bj * 128 + wc * 32 + fq * 8) = o;
;           }
	v_mfma_f32_16x16x32_bf16 v[48:51], v[212:215], v[180:183], v[48:51]
	v_mfma_f32_16x16x32_bf16 v[44:47], v[220:223], v[180:183], v[44:47]
	s_add_i32 s29, s29, 2
	s_add_u32 s20, s20, 0x100
	s_addc_u32 s21, s21, 0
	v_mfma_f32_16x16x32_bf16 v[32:35], v[212:215], v[188:191], v[32:35]
	s_cmp_ge_u32 s33, s49
	s_cselect_b32 s75, 1, 0
	s_mov_b32 s2, s33
	v_mfma_f32_16x16x32_bf16 v[28:31], v[220:223], v[188:191], v[28:31]
	s_cmp_eq_u32 s49, s29
	s_cselect_b64 s[68:69], -1, 0
	s_and_b64 s[64:65], s[68:69], exec
	v_mfma_f32_16x16x32_bf16 v[16:19], v[212:215], v[196:199], v[16:19]
	s_cselect_b32 s52, s10, s8
	s_cselect_b32 s64, s11, s9
	s_add_i32 s33, s2, 2
	v_mfma_f32_16x16x32_bf16 v[12:15], v[220:223], v[196:199], v[12:15]
	s_and_b64 s[68:69], s[68:69], exec
	s_cselect_b32 s71, s15, s21
	s_cselect_b32 s70, s14, s20
	v_mfma_f32_16x16x32_bf16 v[8:11], v[212:215], v[204:207], v[8:11]
	s_cselect_b32 s68, 0, s33
	s_cselect_b32 s65, s12, s16
	s_cselect_b32 s66, s13, s17
	v_mfma_f32_16x16x32_bf16 v[4:7], v[220:223], v[204:207], v[4:7]
	s_or_b32 s2, s2, 1
	s_cmp_lt_u32 s2, s36
	s_cselect_b64 vcc, -1, 0
	v_mfma_f32_16x16x32_bf16 v[48:51], v[216:219], v[184:187], v[48:51]
	s_and_b64 s[2:3], vcc, exec
	s_cselect_b32 s3, 0, s36
	s_cselect_b32 s2, s38, s37
	v_mfma_f32_16x16x32_bf16 v[44:47], v[224:227], v[184:187], v[44:47]
	s_not_b32 s3, s3
	s_add_i32 s94, s3, s29
	s_and_b64 s[72:73], vcc, exec
	v_mfma_f32_16x16x32_bf16 v[32:35], v[216:219], v[192:195], v[32:35]
	s_cselect_b32 s3, s9, s17
	s_cselect_b32 s69, s8, s16
	s_lshl_b64 s[72:73], s[94:95], 7
	v_mfma_f32_16x16x32_bf16 v[28:31], v[224:227], v[192:195], v[28:31]
	s_add_u32 s69, s69, s72
	s_addc_u32 s74, s3, s73
	s_mov_b32 s3, s95
	v_mfma_f32_16x16x32_bf16 v[16:19], v[216:219], v[200:203], v[16:19]
	s_lshl_b64 s[72:73], s[2:3], 8
	s_add_u32 s72, s69, s72
	v_mfma_f32_16x16x32_bf16 v[12:15], v[224:227], v[200:203], v[12:15]
	s_addc_u32 s73, s74, s73
	s_add_i32 m0, s42, 0xc000
	v_mfma_f32_16x16x32_bf16 v[8:11], v[216:219], v[208:211], v[8:11]
	s_lshl_b64 s[2:3], s[2:3], 7
	s_add_u32 s2, s72, s2
	v_mfma_f32_16x16x32_bf16 v[4:7], v[224:227], v[208:211], v[4:7]
	s_addc_u32 s3, s73, s3
	s_cmp_lg_u32 s75, 0
	s_barrier
	s_cbranch_scc0 .LBB0_729
	v_add_u32_e32 v164, s5, v1
	s_ashr_i32 s5, s4, 31
	s_lshl_b64 s[2:3], s[4:5], 1
	v_ashrrev_i32_e32 v2, 31, v164
	s_add_u32 s2, s50, s2
	v_cvt_pk_bf16_f32 v128, v128, v129
	v_cvt_pk_bf16_f32 v129, v130, v131
	v_cvt_pk_bf16_f32 v130, v124, v125
	v_mul_lo_u32 v2, v2, s18
	v_mad_u64_u32 v[124:125], s[4:5], v164, s18, 0
	s_addc_u32 s3, s51, s3
	v_add_u32_e32 v125, v125, v2
	v_lshl_add_u64 v[124:125], v[124:125], 1, s[2:3]
	v_mov_b32_e32 v141, v3
	v_lshl_add_u64 v[124:125], v[124:125], 0, v[140:141]
	v_mov_b32_e32 v143, v3
	v_lshl_add_u64 v[124:125], v[124:125], 0, v[142:143]
	s_lshl_b32 s2, s18, 5
	s_mov_b32 s3, 0
	s_mul_i32 s4, s18, 0xa0
	s_mov_b32 s5, 0
	v_cvt_pk_bf16_f32 v112, v112, v113
	v_cvt_pk_bf16_f32 v113, v114, v115
	v_cvt_pk_bf16_f32 v114, v108, v109
	v_cvt_pk_bf16_f32 v115, v110, v111
	global_store_dwordx4 v[124:125], v[112:115], off offset:256
	v_cvt_pk_bf16_f32 v131, v126, v127
	v_cvt_pk_bf16_f32 v96, v96, v97
	v_lshl_add_u64 v[112:113], v[124:125], 0, s[2:3]
	v_cvt_pk_bf16_f32 v97, v98, v99
	v_cvt_pk_bf16_f32 v98, v92, v93
	v_cvt_pk_bf16_f32 v99, v94, v95
	global_store_dwordx4 v[124:125], v[128:131], off
	global_store_dwordx4 v[112:113], v[96:99], off offset:256
	v_cvt_pk_bf16_f32 v108, v120, v121
	v_cvt_pk_bf16_f32 v109, v122, v123
	v_lshl_add_u64 v[96:97], v[112:113], 0, s[2:3]
	v_cvt_pk_bf16_f32 v110, v116, v117
	v_cvt_pk_bf16_f32 v111, v118, v119
	v_cvt_pk_bf16_f32 v80, v80, v81
	v_cvt_pk_bf16_f32 v81, v82, v83
	v_cvt_pk_bf16_f32 v82, v76, v77
	v_cvt_pk_bf16_f32 v83, v78, v79
	global_store_dwordx4 v[112:113], v[108:111], off
	global_store_dwordx4 v[96:97], v[80:83], off offset:256
	v_cvt_pk_bf16_f32 v64, v64, v65
	v_cvt_pk_bf16_f32 v65, v66, v67
	v_lshl_add_u64 v[80:81], v[96:97], 0, s[2:3]
	v_cvt_pk_bf16_f32 v66, v60, v61
	v_lshl_add_u64 v[60:61], v[80:81], 0, s[4:5]
	v_cvt_pk_bf16_f32 v72, v72, v73
	v_cvt_pk_bf16_f32 v73, v74, v75
	v_cvt_pk_bf16_f32 v74, v68, v69
	v_cvt_pk_bf16_f32 v67, v62, v63
	v_cvt_pk_bf16_f32 v92, v104, v105
	v_cvt_pk_bf16_f32 v93, v106, v107
	v_cvt_pk_bf16_f32 v94, v100, v101
	v_cvt_pk_bf16_f32 v95, v102, v103
	v_cvt_pk_bf16_f32 v76, v88, v89
	v_cvt_pk_bf16_f32 v77, v90, v91
	v_cvt_pk_bf16_f32 v78, v84, v85
	v_cvt_pk_bf16_f32 v79, v86, v87
	v_cvt_pk_bf16_f32 v75, v70, v71
	v_cvt_pk_bf16_f32 v48, v48, v49
	v_cvt_pk_bf16_f32 v49, v50, v51
	v_cvt_pk_bf16_f32 v50, v44, v45
	v_cvt_pk_bf16_f32 v51, v46, v47
	global_store_dwordx4 v[96:97], v[92:95], off
	global_store_dwordx4 v[80:81], v[76:79], off
	global_store_dwordx4 v[80:81], v[72:75], off offset:256
	global_store_dwordx4 v[60:61], v[48:51], off offset:256
	v_cvt_pk_bf16_f32 v32, v32, v33
	v_cvt_pk_bf16_f32 v33, v34, v35
	v_lshl_add_u64 v[48:49], v[60:61], 0, s[2:3]
	v_cvt_pk_bf16_f32 v34, v28, v29
	v_cvt_pk_bf16_f32 v35, v30, v31
	global_store_dwordx4 v[60:61], v[64:67], off
	global_store_dwordx4 v[48:49], v[32:35], off offset:256
	v_cvt_pk_bf16_f32 v44, v56, v57
	v_cvt_pk_bf16_f32 v45, v58, v59
	v_lshl_add_u64 v[32:33], v[48:49], 0, s[2:3]
	v_cvt_pk_bf16_f32 v46, v52, v53
	v_cvt_pk_bf16_f32 v47, v54, v55
	v_cvt_pk_bf16_f32 v16, v16, v17
	v_cvt_pk_bf16_f32 v17, v18, v19
	v_cvt_pk_bf16_f32 v18, v12, v13
	v_cvt_pk_bf16_f32 v19, v14, v15
	global_store_dwordx4 v[48:49], v[44:47], off
	global_store_dwordx4 v[32:33], v[16:19], off offset:256
	v_cvt_pk_bf16_f32 v28, v40, v41
	v_cvt_pk_bf16_f32 v29, v42, v43
	v_lshl_add_u64 v[16:17], v[32:33], 0, s[2:3]
	v_cvt_pk_bf16_f32 v30, v36, v37
	v_cvt_pk_bf16_f32 v31, v38, v39
	v_cvt_pk_bf16_f32 v12, v24, v25
	v_cvt_pk_bf16_f32 v13, v26, v27
	v_cvt_pk_bf16_f32 v14, v20, v21
	v_cvt_pk_bf16_f32 v15, v22, v23
	v_cvt_pk_bf16_f32 v8, v8, v9
	v_cvt_pk_bf16_f32 v9, v10, v11
	v_cvt_pk_bf16_f32 v10, v4, v5
	v_cvt_pk_bf16_f32 v11, v6, v7
	s_and_b64 vcc, exec, s[6:7]
	s_mov_b64 s[2:3], s[14:15]
	s_mov_b64 s[16:17], s[12:13]
	s_mov_b64 s[8:9], s[10:11]
	s_mov_b32 s4, s56
	s_mov_b32 s5, s28
	global_store_dwordx4 v[32:33], v[28:31], off
	global_store_dwordx4 v[16:17], v[12:15], off
	global_store_dwordx4 v[16:17], v[8:11], off offset:256
	s_cbranch_vccz .LBB0_726
	s_waitcnt vmcnt(0)
	s_movk_i32 s66, 0x100
	v_cmp_gt_u32_e32 vcc, s66, v135
	s_and_saveexec_b64 s[0:1], vcc
	s_cbranch_execz .LBB0_733
	s_barrier
